# v111 + FFN-in epilogue stores in saddr form (8 per tile)
# baseline (speedup 1.0000x reference)
.LBB0_1132:
	v_lshl_add_u32 v146, s4, 8, v154
	v_ashrrev_i32_e32 v147, 31, v146
	v_lshl_add_u64 v[164:165], v[146:147], 2, s[10:11]
	v_or_b32_e32 v150, 16, v146
	global_load_dword v163, v[164:165], off
	v_ashrrev_i32_e32 v151, 31, v150
	v_lshl_add_u64 v[144:145], v[150:151], 2, s[10:11]
	global_load_dword v172, v[144:145], off
	v_lshl_or_b32 v166, s5, 7, v156
	v_or_b32_e32 v152, 32, v146
	v_mov_b64_e32 v[144:145], s[12:13]
	v_or_b32_e32 v148, 48, v146
	v_ashrrev_i32_e32 v167, 31, v166
	v_ashrrev_i32_e32 v153, 31, v152
	v_add_u32_e32 v178, 0x80, v146
	v_add_u32_e32 v162, 0x90, v146
	v_add_u32_e32 v161, 0xa0, v146
	v_add_u32_e32 v151, 0xb0, v146
	v_mul_u32_u24_e32 v168, s51, v146
	v_ashrrev_i32_e32 v149, 31, v148
	v_lshlrev_b64 v[146:147], 1, v[166:167]
	v_lshl_add_u64 v[166:167], v[152:153], 2, s[10:11]
	v_lshl_add_u64 v[170:171], v[148:149], 2, s[10:11]
	global_load_dword v179, v[164:165], off offset:512
	global_load_dword v180, v[164:165], off offset:576
	global_load_dword v153, v[164:165], off offset:640
	s_nop 0
	global_load_dword v167, v[166:167], off
	s_nop 0
	global_load_dword v181, v[170:171], off
	global_load_dword v149, v[164:165], off offset:704
	s_waitcnt vmcnt(0)
	v_fmamk_f32 v163, v163, 0x3a800000, v160
	v_mul_f32_e32 v164, 0x4b800000, v163
	v_cmp_gt_f32_e32 vcc, s50, v163
	v_fmamk_f32 v165, v172, 0x3a800000, v160
	v_cmp_gt_f32_e64 s[4:5], s50, v165
	v_cndmask_b32_e32 v163, v163, v164, vcc
	v_mul_f32_e32 v164, 0x4b800000, v165
	v_rsq_f32_e32 v163, v163
	v_cndmask_b32_e64 v164, v165, v164, s[4:5]
	v_rsq_f32_e32 v170, v164
	v_add_u32_e32 v164, v168, v146
	v_mul_f32_e32 v166, 0x45800000, v163
	v_cndmask_b32_e32 v166, v163, v166, vcc
	v_mul_f32_e32 v163, 0x45800000, v170
	v_pk_mul_f32 v[124:125], v[124:125], v[166:167] op_sel_hi:[1,0]
	v_pk_mul_f32 v[126:127], v[126:127], v[166:167] op_sel_hi:[1,0]
	v_pk_mul_f32 v[120:121], v[120:121], v[166:167] op_sel_hi:[1,0]
	v_pk_mul_f32 v[122:123], v[122:123], v[166:167] op_sel_hi:[1,0]
	v_pk_mul_f32 v[116:117], v[116:117], v[166:167] op_sel_hi:[1,0]
	v_pk_mul_f32 v[118:119], v[118:119], v[166:167] op_sel_hi:[1,0]
	v_pk_mul_f32 v[112:113], v[112:113], v[166:167] op_sel_hi:[1,0]
	v_pk_mul_f32 v[114:115], v[114:115], v[166:167] op_sel_hi:[1,0]
	v_cndmask_b32_e64 v166, v170, v163, s[4:5]
	v_mul_f32_e32 v163, 0xbfb8aa3b, v124
	v_mul_f32_e32 v168, 0xbfb8aa3b, v125
	v_mul_f32_e32 v169, 0xbfb8aa3b, v126
	v_mul_f32_e32 v170, 0xbfb8aa3b, v127
	v_mul_f32_e32 v171, 0xbfb8aa3b, v120
	v_mul_f32_e32 v172, 0xbfb8aa3b, v121
	v_mul_f32_e32 v173, 0xbfb8aa3b, v122
	v_mul_f32_e32 v174, 0xbfb8aa3b, v123
	v_exp_f32_e32 v163, v163
	v_exp_f32_e32 v168, v168
	v_exp_f32_e32 v169, v169
	v_exp_f32_e32 v170, v170
	v_exp_f32_e32 v171, v171
	v_exp_f32_e32 v172, v172
	v_exp_f32_e32 v173, v173
	v_exp_f32_e32 v174, v174
	v_pk_mul_f32 v[108:109], v[108:109], v[166:167] op_sel_hi:[1,0]
	v_add_f32_e32 v163, 1.0, v163
	v_mul_f32_e32 v175, 0xbfb8aa3b, v108
	v_exp_f32_e32 v177, v175
	v_add_f32_e32 v175, 1.0, v168
	v_add_f32_e32 v182, 1.0, v169
	v_add_f32_e32 v183, 1.0, v170
	v_add_f32_e32 v184, 1.0, v171
	v_add_f32_e32 v185, 1.0, v172
	v_add_f32_e32 v186, 1.0, v173
	v_add_f32_e32 v187, 1.0, v174
	v_rcp_f32_e32 v168, v163
	v_rcp_f32_e32 v169, v175
	v_rcp_f32_e32 v170, v182
	v_rcp_f32_e32 v171, v183
	v_rcp_f32_e32 v172, v184
	v_rcp_f32_e32 v173, v185
	v_rcp_f32_e32 v174, v186
	v_rcp_f32_e32 v175, v187
	v_pk_mul_f32 v[124:125], v[124:125], v[168:169]
	v_pk_mul_f32 v[126:127], v[126:127], v[170:171]
	v_pk_mul_f32 v[120:121], v[120:121], v[172:173]
	v_pk_mul_f32 v[122:123], v[122:123], v[174:175]
	v_pk_mul_f32 v[116:117], v[116:117], v[124:125]
	v_pk_mul_f32 v[118:119], v[118:119], v[126:127]
	v_pk_mul_f32 v[120:121], v[112:113], v[120:121]
	v_pk_mul_f32 v[122:123], v[114:115], v[122:123]
	v_mul_f32_e32 v176, 0xbfb8aa3b, v109
	v_cvt_pk_bf16_f32 v112, v116, v117
	v_cvt_pk_bf16_f32 v113, v118, v119
	v_cvt_pk_bf16_f32 v114, v120, v121
	v_cvt_pk_bf16_f32 v115, v122, v123
	v_pk_mul_f32 v[110:111], v[110:111], v[166:167] op_sel_hi:[1,0]
	v_exp_f32_e32 v176, v176
	global_store_dwordx4 v164, v[112:115], s[12:13]
	v_add_f32_e32 v163, 1.0, v177
	v_pk_mul_f32 v[100:101], v[100:101], v[166:167] op_sel_hi:[1,0]
	v_mul_f32_e32 v112, 0xbfb8aa3b, v110
	v_mul_f32_e32 v113, 0xbfb8aa3b, v111
	v_exp_f32_e32 v112, v112
	v_exp_f32_e32 v113, v113
	v_add_f32_e32 v177, 1.0, v176
	v_rcp_f32_e32 v176, v163
	v_rcp_f32_e32 v177, v177
	v_add_f32_e32 v112, 1.0, v112
	v_add_f32_e32 v113, 1.0, v113
	v_rcp_f32_e32 v112, v112
	v_rcp_f32_e32 v113, v113
	v_pk_mul_f32 v[108:109], v[108:109], v[176:177]
	v_pk_mul_f32 v[104:105], v[104:105], v[166:167] op_sel_hi:[1,0]
	v_pk_mul_f32 v[100:101], v[100:101], v[108:109]
	v_pk_mul_f32 v[108:109], v[110:111], v[112:113]
	v_mul_f32_e32 v110, 0xbfb8aa3b, v104
	v_exp_f32_e32 v110, v110
	v_pk_mul_f32 v[102:103], v[102:103], v[166:167] op_sel_hi:[1,0]
	v_pk_mul_f32 v[106:107], v[106:107], v[166:167] op_sel_hi:[1,0]
	v_pk_mul_f32 v[102:103], v[102:103], v[108:109]
	v_mul_f32_e32 v108, 0xbfb8aa3b, v105
	v_exp_f32_e32 v109, v108
	v_add_f32_e32 v108, 1.0, v110
	v_mul_f32_e32 v110, 0xbfb8aa3b, v106
	v_mul_f32_e32 v111, 0xbfb8aa3b, v107
	v_exp_f32_e32 v110, v110
	v_exp_f32_e32 v111, v111
	v_add_f32_e32 v109, 1.0, v109
	v_rcp_f32_e32 v108, v108
	v_rcp_f32_e32 v109, v109
	v_add_f32_e32 v110, 1.0, v110
	v_add_f32_e32 v111, 1.0, v111
	v_rcp_f32_e32 v110, v110
	v_rcp_f32_e32 v111, v111
	v_pk_mul_f32 v[96:97], v[96:97], v[166:167] op_sel_hi:[1,0]
	v_pk_mul_f32 v[104:105], v[104:105], v[108:109]
	s_nop 0
	v_pk_mul_f32 v[104:105], v[96:97], v[104:105]
	v_pk_mul_f32 v[96:97], v[98:99], v[166:167] op_sel_hi:[1,0]
	v_pk_mul_f32 v[98:99], v[106:107], v[110:111]
	s_nop 0
	v_pk_mul_f32 v[106:107], v[96:97], v[98:99]
	v_cvt_pk_bf16_f32 v96, v100, v101
	v_fmamk_f32 v100, v167, 0x3a800000, v160
	v_mul_f32_e32 v101, 0x4b800000, v100
	v_cmp_gt_f32_e32 vcc, s50, v100
	v_cvt_pk_bf16_f32 v97, v102, v103
	v_cvt_pk_bf16_f32 v98, v104, v105
	v_cndmask_b32_e32 v100, v100, v101, vcc
	v_rsq_f32_e32 v102, v100
	v_mad_u32_u24 v100, v150, s51, v146
	v_cvt_pk_bf16_f32 v99, v106, v107
	v_mul_f32_e32 v103, 0x45800000, v102
	v_cndmask_b32_e32 v102, v102, v103, vcc
	v_pk_mul_f32 v[92:93], v[92:93], v[102:103] op_sel_hi:[1,0]
	s_nop 0
	v_mul_f32_e32 v103, 0xbfb8aa3b, v92
	v_exp_f32_e32 v103, v103
	global_store_dwordx4 v100, v[96:99], s[12:13]
	v_pk_mul_f32 v[94:95], v[94:95], v[102:103] op_sel_hi:[1,0]
	s_nop 0
	v_mul_f32_e32 v96, 0xbfb8aa3b, v93
	v_exp_f32_e32 v97, v96
	v_mul_f32_e32 v98, 0xbfb8aa3b, v94
	v_mul_f32_e32 v99, 0xbfb8aa3b, v95
	v_exp_f32_e32 v98, v98
	v_exp_f32_e32 v99, v99
	v_add_f32_e32 v96, 1.0, v103
	v_add_f32_e32 v97, 1.0, v97
	v_rcp_f32_e32 v96, v96
	v_rcp_f32_e32 v97, v97
	v_add_f32_e32 v98, 1.0, v98
	v_add_f32_e32 v99, 1.0, v99
	v_rcp_f32_e32 v98, v98
	v_rcp_f32_e32 v99, v99
	v_pk_mul_f32 v[84:85], v[84:85], v[102:103] op_sel_hi:[1,0]
	v_pk_mul_f32 v[92:93], v[92:93], v[96:97]
	v_pk_mul_f32 v[88:89], v[88:89], v[102:103] op_sel_hi:[1,0]
	v_pk_mul_f32 v[84:85], v[84:85], v[92:93]
	v_pk_mul_f32 v[92:93], v[94:95], v[98:99]
	v_mul_f32_e32 v94, 0xbfb8aa3b, v88
	v_exp_f32_e32 v94, v94
	v_pk_mul_f32 v[86:87], v[86:87], v[102:103] op_sel_hi:[1,0]
	v_pk_mul_f32 v[90:91], v[90:91], v[102:103] op_sel_hi:[1,0]
	v_pk_mul_f32 v[86:87], v[86:87], v[92:93]
	v_mul_f32_e32 v92, 0xbfb8aa3b, v89
	v_exp_f32_e32 v93, v92
	v_add_f32_e32 v92, 1.0, v94
	v_mul_f32_e32 v94, 0xbfb8aa3b, v90
	v_mul_f32_e32 v95, 0xbfb8aa3b, v91
	v_exp_f32_e32 v94, v94
	v_exp_f32_e32 v95, v95
	v_add_f32_e32 v93, 1.0, v93
	v_rcp_f32_e32 v92, v92
	v_rcp_f32_e32 v93, v93
	v_add_f32_e32 v94, 1.0, v94
	v_add_f32_e32 v95, 1.0, v95
	v_rcp_f32_e32 v94, v94
	v_rcp_f32_e32 v95, v95
	v_pk_mul_f32 v[80:81], v[80:81], v[102:103] op_sel_hi:[1,0]
	v_pk_mul_f32 v[88:89], v[88:89], v[92:93]
	s_nop 0
	v_pk_mul_f32 v[88:89], v[80:81], v[88:89]
	v_pk_mul_f32 v[80:81], v[82:83], v[102:103] op_sel_hi:[1,0]
	v_pk_mul_f32 v[82:83], v[90:91], v[94:95]
	s_nop 0
	v_pk_mul_f32 v[90:91], v[80:81], v[82:83]
	v_cvt_pk_bf16_f32 v80, v84, v85
	v_fmamk_f32 v84, v181, 0x3a800000, v160
	v_mul_f32_e32 v85, 0x4b800000, v84
	v_cmp_gt_f32_e32 vcc, s50, v84
	v_cvt_pk_bf16_f32 v81, v86, v87
	v_cvt_pk_bf16_f32 v82, v88, v89
	v_cndmask_b32_e32 v84, v84, v85, vcc
	v_rsq_f32_e32 v86, v84
	v_mad_u32_u24 v84, v152, s51, v146
	v_cvt_pk_bf16_f32 v83, v90, v91
	v_mul_f32_e32 v87, 0x45800000, v86
	v_cndmask_b32_e32 v86, v86, v87, vcc
	v_pk_mul_f32 v[76:77], v[76:77], v[86:87] op_sel_hi:[1,0]
	s_nop 0
	v_mul_f32_e32 v87, 0xbfb8aa3b, v76
	v_exp_f32_e32 v87, v87
	global_store_dwordx4 v84, v[80:83], s[12:13]
	v_pk_mul_f32 v[78:79], v[78:79], v[86:87] op_sel_hi:[1,0]
	s_nop 0
	v_mul_f32_e32 v80, 0xbfb8aa3b, v77
	v_exp_f32_e32 v81, v80
	v_mul_f32_e32 v82, 0xbfb8aa3b, v78
	v_mul_f32_e32 v83, 0xbfb8aa3b, v79
	v_exp_f32_e32 v82, v82
	v_exp_f32_e32 v83, v83
	v_add_f32_e32 v80, 1.0, v87
	v_add_f32_e32 v81, 1.0, v81
	v_rcp_f32_e32 v80, v80
	v_rcp_f32_e32 v81, v81
	v_add_f32_e32 v82, 1.0, v82
	v_add_f32_e32 v83, 1.0, v83
	v_rcp_f32_e32 v82, v82
	v_rcp_f32_e32 v83, v83
	v_pk_mul_f32 v[68:69], v[68:69], v[86:87] op_sel_hi:[1,0]
	v_pk_mul_f32 v[76:77], v[76:77], v[80:81]
	v_pk_mul_f32 v[72:73], v[72:73], v[86:87] op_sel_hi:[1,0]
	v_pk_mul_f32 v[68:69], v[68:69], v[76:77]
	v_pk_mul_f32 v[76:77], v[78:79], v[82:83]
	v_mul_f32_e32 v78, 0xbfb8aa3b, v72
	v_exp_f32_e32 v78, v78
	v_pk_mul_f32 v[70:71], v[70:71], v[86:87] op_sel_hi:[1,0]
	v_pk_mul_f32 v[74:75], v[74:75], v[86:87] op_sel_hi:[1,0]
	v_pk_mul_f32 v[70:71], v[70:71], v[76:77]
	v_mul_f32_e32 v76, 0xbfb8aa3b, v73
	v_exp_f32_e32 v77, v76
	v_add_f32_e32 v76, 1.0, v78
	v_mul_f32_e32 v78, 0xbfb8aa3b, v74
	v_mul_f32_e32 v79, 0xbfb8aa3b, v75
	v_exp_f32_e32 v78, v78
	v_exp_f32_e32 v79, v79
	v_add_f32_e32 v77, 1.0, v77
	v_rcp_f32_e32 v76, v76
	v_rcp_f32_e32 v77, v77
	v_add_f32_e32 v78, 1.0, v78
	v_add_f32_e32 v79, 1.0, v79
	v_rcp_f32_e32 v78, v78
	v_rcp_f32_e32 v79, v79
	v_pk_mul_f32 v[64:65], v[64:65], v[86:87] op_sel_hi:[1,0]
	v_pk_mul_f32 v[72:73], v[72:73], v[76:77]
	s_nop 0
	v_pk_mul_f32 v[72:73], v[64:65], v[72:73]
	v_pk_mul_f32 v[64:65], v[66:67], v[86:87] op_sel_hi:[1,0]
	v_pk_mul_f32 v[66:67], v[74:75], v[78:79]
	s_nop 0
	v_pk_mul_f32 v[74:75], v[64:65], v[66:67]
	v_cvt_pk_bf16_f32 v64, v68, v69
	v_fmamk_f32 v68, v179, 0x3a800000, v160
	v_mul_f32_e32 v69, 0x4b800000, v68
	v_cmp_gt_f32_e32 vcc, s50, v68
	v_cvt_pk_bf16_f32 v65, v70, v71
	v_cvt_pk_bf16_f32 v66, v72, v73
	v_cndmask_b32_e32 v68, v68, v69, vcc
	v_rsq_f32_e32 v70, v68
	v_mad_u32_u24 v68, v148, s51, v146
	v_cvt_pk_bf16_f32 v67, v74, v75
	v_mul_f32_e32 v71, 0x45800000, v70
	v_cndmask_b32_e32 v70, v70, v71, vcc
	v_pk_mul_f32 v[60:61], v[60:61], v[70:71] op_sel_hi:[1,0]
	s_nop 0
	v_mul_f32_e32 v71, 0xbfb8aa3b, v60
	v_exp_f32_e32 v71, v71
	global_store_dwordx4 v68, v[64:67], s[12:13]
	v_pk_mul_f32 v[62:63], v[62:63], v[70:71] op_sel_hi:[1,0]
	s_nop 0
	v_mul_f32_e32 v64, 0xbfb8aa3b, v61
	v_exp_f32_e32 v65, v64
	v_mul_f32_e32 v66, 0xbfb8aa3b, v62
	v_mul_f32_e32 v67, 0xbfb8aa3b, v63
	v_exp_f32_e32 v66, v66
	v_exp_f32_e32 v67, v67
	v_add_f32_e32 v64, 1.0, v71
	v_add_f32_e32 v65, 1.0, v65
	v_rcp_f32_e32 v64, v64
	v_rcp_f32_e32 v65, v65
	v_add_f32_e32 v66, 1.0, v66
	v_add_f32_e32 v67, 1.0, v67
	v_rcp_f32_e32 v66, v66
	v_rcp_f32_e32 v67, v67
	v_pk_mul_f32 v[52:53], v[52:53], v[70:71] op_sel_hi:[1,0]
	v_pk_mul_f32 v[60:61], v[60:61], v[64:65]
	v_pk_mul_f32 v[56:57], v[56:57], v[70:71] op_sel_hi:[1,0]
	v_pk_mul_f32 v[52:53], v[52:53], v[60:61]
	v_pk_mul_f32 v[60:61], v[62:63], v[66:67]
	v_mul_f32_e32 v62, 0xbfb8aa3b, v56
	v_exp_f32_e32 v62, v62
	v_pk_mul_f32 v[54:55], v[54:55], v[70:71] op_sel_hi:[1,0]
	v_pk_mul_f32 v[58:59], v[58:59], v[70:71] op_sel_hi:[1,0]
	v_pk_mul_f32 v[54:55], v[54:55], v[60:61]
	v_mul_f32_e32 v60, 0xbfb8aa3b, v57
	v_exp_f32_e32 v61, v60
	v_add_f32_e32 v60, 1.0, v62
	v_mul_f32_e32 v62, 0xbfb8aa3b, v58
	v_mul_f32_e32 v63, 0xbfb8aa3b, v59
	v_exp_f32_e32 v62, v62
	v_exp_f32_e32 v63, v63
	v_add_f32_e32 v61, 1.0, v61
	v_rcp_f32_e32 v60, v60
	v_rcp_f32_e32 v61, v61
	v_add_f32_e32 v62, 1.0, v62
	v_add_f32_e32 v63, 1.0, v63
	v_rcp_f32_e32 v62, v62
	v_rcp_f32_e32 v63, v63
	v_pk_mul_f32 v[48:49], v[48:49], v[70:71] op_sel_hi:[1,0]
	v_pk_mul_f32 v[56:57], v[56:57], v[60:61]
	s_nop 0
	v_pk_mul_f32 v[56:57], v[48:49], v[56:57]
	v_pk_mul_f32 v[48:49], v[50:51], v[70:71] op_sel_hi:[1,0]
	v_pk_mul_f32 v[50:51], v[58:59], v[62:63]
	s_nop 0
	v_pk_mul_f32 v[58:59], v[48:49], v[50:51]
	v_cvt_pk_bf16_f32 v48, v52, v53
	v_fmamk_f32 v52, v180, 0x3a800000, v160
	v_mul_f32_e32 v53, 0x4b800000, v52
	v_cmp_gt_f32_e32 vcc, s50, v52
	v_cvt_pk_bf16_f32 v49, v54, v55
	v_cvt_pk_bf16_f32 v50, v56, v57
	v_cndmask_b32_e32 v52, v52, v53, vcc
	v_rsq_f32_e32 v54, v52
	v_mad_u32_u24 v52, v178, s51, v146
	v_cvt_pk_bf16_f32 v51, v58, v59
	v_mul_f32_e32 v55, 0x45800000, v54
	v_cndmask_b32_e32 v54, v54, v55, vcc
	v_pk_mul_f32 v[44:45], v[44:45], v[54:55] op_sel_hi:[1,0]
	s_nop 0
	v_mul_f32_e32 v55, 0xbfb8aa3b, v44
	v_exp_f32_e32 v55, v55
	global_store_dwordx4 v52, v[48:51], s[12:13]
	v_pk_mul_f32 v[46:47], v[46:47], v[54:55] op_sel_hi:[1,0]
	s_nop 0
	v_mul_f32_e32 v48, 0xbfb8aa3b, v45
	v_exp_f32_e32 v49, v48
	v_mul_f32_e32 v50, 0xbfb8aa3b, v46
	v_mul_f32_e32 v51, 0xbfb8aa3b, v47
	v_exp_f32_e32 v50, v50
	v_exp_f32_e32 v51, v51
	v_add_f32_e32 v48, 1.0, v55
	v_add_f32_e32 v49, 1.0, v49
	v_rcp_f32_e32 v48, v48
	v_rcp_f32_e32 v49, v49
	v_add_f32_e32 v50, 1.0, v50
	v_add_f32_e32 v51, 1.0, v51
	v_rcp_f32_e32 v50, v50
	v_rcp_f32_e32 v51, v51
	v_pk_mul_f32 v[36:37], v[36:37], v[54:55] op_sel_hi:[1,0]
	v_pk_mul_f32 v[44:45], v[44:45], v[48:49]
	v_pk_mul_f32 v[40:41], v[40:41], v[54:55] op_sel_hi:[1,0]
	v_pk_mul_f32 v[36:37], v[36:37], v[44:45]
	v_pk_mul_f32 v[44:45], v[46:47], v[50:51]
	v_mul_f32_e32 v46, 0xbfb8aa3b, v40
	v_exp_f32_e32 v46, v46
	v_pk_mul_f32 v[38:39], v[38:39], v[54:55] op_sel_hi:[1,0]
	v_pk_mul_f32 v[42:43], v[42:43], v[54:55] op_sel_hi:[1,0]
	v_pk_mul_f32 v[38:39], v[38:39], v[44:45]
	v_mul_f32_e32 v44, 0xbfb8aa3b, v41
	v_exp_f32_e32 v45, v44
	v_add_f32_e32 v44, 1.0, v46
	v_mul_f32_e32 v46, 0xbfb8aa3b, v42
	v_mul_f32_e32 v47, 0xbfb8aa3b, v43
	v_exp_f32_e32 v46, v46
	v_exp_f32_e32 v47, v47
	v_add_f32_e32 v45, 1.0, v45
	v_rcp_f32_e32 v44, v44
	v_rcp_f32_e32 v45, v45
	v_add_f32_e32 v46, 1.0, v46
	v_add_f32_e32 v47, 1.0, v47
	v_rcp_f32_e32 v46, v46
	v_rcp_f32_e32 v47, v47
	v_pk_mul_f32 v[32:33], v[32:33], v[54:55] op_sel_hi:[1,0]
	v_pk_mul_f32 v[40:41], v[40:41], v[44:45]
	s_nop 0
	v_pk_mul_f32 v[40:41], v[32:33], v[40:41]
	v_pk_mul_f32 v[32:33], v[34:35], v[54:55] op_sel_hi:[1,0]
	v_pk_mul_f32 v[34:35], v[42:43], v[46:47]
	s_nop 0
	v_pk_mul_f32 v[42:43], v[32:33], v[34:35]
	v_cvt_pk_bf16_f32 v32, v36, v37
	v_fmamk_f32 v36, v153, 0x3a800000, v160
	v_mul_f32_e32 v37, 0x4b800000, v36
	v_cmp_gt_f32_e32 vcc, s50, v36
	v_cvt_pk_bf16_f32 v33, v38, v39
	v_cvt_pk_bf16_f32 v34, v40, v41
	v_cndmask_b32_e32 v36, v36, v37, vcc
	v_rsq_f32_e32 v38, v36
	v_mad_u32_u24 v36, v162, s51, v146
	v_cvt_pk_bf16_f32 v35, v42, v43
	v_mul_f32_e32 v39, 0x45800000, v38
	v_cndmask_b32_e32 v38, v38, v39, vcc
	v_pk_mul_f32 v[28:29], v[28:29], v[38:39] op_sel_hi:[1,0]
	s_nop 0
	v_mul_f32_e32 v39, 0xbfb8aa3b, v28
	v_exp_f32_e32 v39, v39
	global_store_dwordx4 v36, v[32:35], s[12:13]
	v_pk_mul_f32 v[30:31], v[30:31], v[38:39] op_sel_hi:[1,0]
	s_nop 0
	v_mul_f32_e32 v32, 0xbfb8aa3b, v29
	v_exp_f32_e32 v33, v32
	v_mul_f32_e32 v34, 0xbfb8aa3b, v30
	v_mul_f32_e32 v35, 0xbfb8aa3b, v31
	v_exp_f32_e32 v34, v34
	v_exp_f32_e32 v35, v35
	v_add_f32_e32 v32, 1.0, v39
	v_add_f32_e32 v33, 1.0, v33
	v_rcp_f32_e32 v32, v32
	v_rcp_f32_e32 v33, v33
	v_add_f32_e32 v34, 1.0, v34
	v_add_f32_e32 v35, 1.0, v35
	v_rcp_f32_e32 v34, v34
	v_rcp_f32_e32 v35, v35
	v_pk_mul_f32 v[20:21], v[20:21], v[38:39] op_sel_hi:[1,0]
	v_pk_mul_f32 v[28:29], v[28:29], v[32:33]
	v_pk_mul_f32 v[24:25], v[24:25], v[38:39] op_sel_hi:[1,0]
	v_pk_mul_f32 v[20:21], v[20:21], v[28:29]
	v_pk_mul_f32 v[28:29], v[30:31], v[34:35]
	v_mul_f32_e32 v30, 0xbfb8aa3b, v24
	v_exp_f32_e32 v30, v30
	v_pk_mul_f32 v[22:23], v[22:23], v[38:39] op_sel_hi:[1,0]
	v_pk_mul_f32 v[26:27], v[26:27], v[38:39] op_sel_hi:[1,0]
	v_pk_mul_f32 v[22:23], v[22:23], v[28:29]
	v_mul_f32_e32 v28, 0xbfb8aa3b, v25
	v_exp_f32_e32 v29, v28
	v_add_f32_e32 v28, 1.0, v30
	v_mul_f32_e32 v30, 0xbfb8aa3b, v26
	v_mul_f32_e32 v31, 0xbfb8aa3b, v27
	v_exp_f32_e32 v30, v30
	v_exp_f32_e32 v31, v31
	v_add_f32_e32 v29, 1.0, v29
	v_rcp_f32_e32 v28, v28
	v_rcp_f32_e32 v29, v29
	v_add_f32_e32 v30, 1.0, v30
	v_add_f32_e32 v31, 1.0, v31
	v_rcp_f32_e32 v30, v30
	v_rcp_f32_e32 v31, v31
	v_pk_mul_f32 v[16:17], v[16:17], v[38:39] op_sel_hi:[1,0]
	v_pk_mul_f32 v[24:25], v[24:25], v[28:29]
	s_nop 0
	v_pk_mul_f32 v[24:25], v[16:17], v[24:25]
	v_pk_mul_f32 v[16:17], v[18:19], v[38:39] op_sel_hi:[1,0]
	v_pk_mul_f32 v[18:19], v[26:27], v[30:31]
	s_nop 0
	v_pk_mul_f32 v[26:27], v[16:17], v[18:19]
	v_cvt_pk_bf16_f32 v16, v20, v21
	v_fmamk_f32 v20, v149, 0x3a800000, v160
	v_mul_f32_e32 v21, 0x4b800000, v20
	v_cmp_gt_f32_e32 vcc, s50, v20
	v_cvt_pk_bf16_f32 v17, v22, v23
	v_cvt_pk_bf16_f32 v18, v24, v25
	v_cndmask_b32_e32 v20, v20, v21, vcc
	v_rsq_f32_e32 v22, v20
	v_mad_u32_u24 v20, v161, s51, v146
	v_cvt_pk_bf16_f32 v19, v26, v27
	v_mul_f32_e32 v23, 0x45800000, v22
	v_cndmask_b32_e32 v22, v22, v23, vcc
	v_pk_mul_f32 v[12:13], v[12:13], v[22:23] op_sel_hi:[1,0]
	s_nop 0
	v_mul_f32_e32 v23, 0xbfb8aa3b, v12
	v_exp_f32_e32 v23, v23
	global_store_dwordx4 v20, v[16:19], s[12:13]
	s_andn2_b64 vcc, exec, s[0:1]
	s_mov_b64 s[0:1], -1
	v_mul_f32_e32 v16, 0xbfb8aa3b, v13
	v_pk_mul_f32 v[14:15], v[14:15], v[22:23] op_sel_hi:[1,0]
	v_exp_f32_e32 v17, v16
	v_mul_f32_e32 v18, 0xbfb8aa3b, v14
	v_mul_f32_e32 v19, 0xbfb8aa3b, v15
	v_exp_f32_e32 v18, v18
	v_exp_f32_e32 v19, v19
	v_add_f32_e32 v16, 1.0, v23
	v_add_f32_e32 v17, 1.0, v17
	v_rcp_f32_e32 v16, v16
	v_rcp_f32_e32 v17, v17
	v_add_f32_e32 v18, 1.0, v18
	v_add_f32_e32 v19, 1.0, v19
	v_rcp_f32_e32 v18, v18
	v_rcp_f32_e32 v19, v19
	v_pk_mul_f32 v[4:5], v[4:5], v[22:23] op_sel_hi:[1,0]
	v_pk_mul_f32 v[12:13], v[12:13], v[16:17]
	v_pk_mul_f32 v[8:9], v[8:9], v[22:23] op_sel_hi:[1,0]
	v_pk_mul_f32 v[4:5], v[4:5], v[12:13]
	v_pk_mul_f32 v[12:13], v[14:15], v[18:19]
	v_mul_f32_e32 v14, 0xbfb8aa3b, v8
	v_exp_f32_e32 v14, v14
	v_pk_mul_f32 v[6:7], v[6:7], v[22:23] op_sel_hi:[1,0]
	v_pk_mul_f32 v[10:11], v[10:11], v[22:23] op_sel_hi:[1,0]
	v_pk_mul_f32 v[6:7], v[6:7], v[12:13]
	v_mul_f32_e32 v12, 0xbfb8aa3b, v9
	v_exp_f32_e32 v13, v12
	v_add_f32_e32 v12, 1.0, v14
	v_mul_f32_e32 v14, 0xbfb8aa3b, v10
	v_mul_f32_e32 v15, 0xbfb8aa3b, v11
	v_exp_f32_e32 v14, v14
	v_exp_f32_e32 v15, v15
	v_add_f32_e32 v13, 1.0, v13
	v_rcp_f32_e32 v12, v12
	v_rcp_f32_e32 v13, v13
	v_add_f32_e32 v14, 1.0, v14
	v_add_f32_e32 v15, 1.0, v15
	v_rcp_f32_e32 v14, v14
	v_rcp_f32_e32 v15, v15
	v_pk_mul_f32 v[0:1], v[0:1], v[22:23] op_sel_hi:[1,0]
	v_pk_mul_f32 v[8:9], v[8:9], v[12:13]
	s_nop 0
	v_pk_mul_f32 v[8:9], v[0:1], v[8:9]
	v_pk_mul_f32 v[0:1], v[2:3], v[22:23] op_sel_hi:[1,0]
	v_pk_mul_f32 v[2:3], v[10:11], v[14:15]
	s_nop 0
	v_pk_mul_f32 v[10:11], v[0:1], v[2:3]
	v_cvt_pk_bf16_f32 v0, v4, v5
	v_mad_u32_u24 v4, v151, s51, v146
	v_cvt_pk_bf16_f32 v1, v6, v7
	v_cvt_pk_bf16_f32 v2, v8, v9
	v_cvt_pk_bf16_f32 v3, v10, v11
	s_nop 0
	global_store_dwordx4 v4, v[0:3], s[12:13]
	s_cbranch_vccnz .LBB0_1125
	s_andn2_b64 vcc, exec, s[8:9]
	s_cbranch_vccnz .LBB0_1124
	s_barrier
	s_branch .LBB0_1124
